# v6 plus K-range trimming of the lora-up GEMM (skips the structurally zero k tiles of the block matrix: 10 instead of 24 k tiles per 4 planes)
# speedup vs baseline: 1.0177x; 1.0095x over previous
.LBB0_259:
	v_writelane_b32 v255, s52, 34
	s_ashr_i32 s2, s0, 6
	v_mul_lo_u32 v0, s48, v161
	v_writelane_b32 v255, s53, 35
	v_writelane_b32 v255, s50, 36
	s_lshl_b32 s3, s2, 10
	v_add_lshl_u32 v217, v0, v163, 1
	v_writelane_b32 v255, s51, 37
	v_mul_lo_u32 v0, s49, v208
	s_add_i32 s70, s3, 0
	v_add_lshl_u32 v218, v0, v163, 1
	v_mul_lo_u32 v0, s48, v209
	v_writelane_b32 v255, s48, 38
	s_lshl_b32 s9, s49, 9
	s_add_i32 s71, s70, 0x10000
	v_add_lshl_u32 v219, v0, v210, 1
	v_mul_lo_u32 v0, s49, v211
	s_lshl_b32 s73, s48, 8
	s_lshl_b32 s64, s49, 8
	s_lshl_b32 s65, s48, 9
	v_writelane_b32 v255, s49, 39
	s_and_b32 s49, s95, 0xffff
	s_mov_b32 s48, s94
	s_mov_b32 s50, s78
	s_mov_b32 s51, s79
	s_mul_i32 s44, s33, s9
	s_lshr_b32 s32, s33, 2
	s_sub_i32 s32, s32, 1
	s_max_i32 s32, s32, 0
	s_lshl_b32 s32, s32, 8
	s_cmp_eq_u32 s16, 3
	s_cselect_b32 s32, s32, 0
	s_add_i32 s44, s44, s32
	s_mov_b32 m0, s71
	s_add_i32 s28, s70, 0x12000
	v_add_lshl_u32 v220, v0, v210, 1
	buffer_load_dwordx4 v218, s[48:51], s44 offen lds
	s_mov_b32 m0, s28
	s_add_i32 s29, s70, 0x14000
	buffer_load_dwordx4 v220, s[48:51], s44 offen lds
	s_add_i32 s3, s44, s64
	s_mov_b32 m0, s29
	s_add_i32 s26, s70, 0x16000
	s_mul_i32 s18, s72, s33
	s_mul_i32 s19, s87, s65
	buffer_load_dwordx4 v218, s[48:51], s3 offen lds
	s_mov_b32 m0, s26
	s_and_b32 s77, s47, 0xffff
	s_mov_b32 s76, s46
	buffer_load_dwordx4 v220, s[48:51], s3 offen lds
	s_add_i32 s45, s18, s19
	s_add_i32 s45, s45, s32
	s_mov_b32 m0, s70
	s_add_i32 s27, s70, 0x2000
	buffer_load_dwordx4 v217, s[76:79], s45 offen lds
	s_mov_b32 m0, s27
	s_add_i32 s62, s70, 0x4000
	buffer_load_dwordx4 v219, s[76:79], s45 offen lds
	s_add_i32 s18, s45, s73
	s_mov_b32 m0, s62
	s_add_i32 s63, s70, 0x6000
	buffer_load_dwordx4 v217, s[76:79], s18 offen lds
	s_mov_b32 m0, s63
	s_cmp_eq_u32 s1, 1
	buffer_load_dwordx4 v219, s[76:79], s18 offen lds
	s_cselect_b64 s[52:53], -1, 0
	s_cmp_lg_u32 s1, 1
	s_cbranch_scc1 .LBB0_261
	s_barrier

.LBB0_267:
	s_nop 0
	v_cndmask_b32_e64 v0, 0, 1, s[42:43]
	v_cmp_ne_u32_e64 s[40:41], 1, v0
	s_andn2_b64 vcc, exec, s[42:43]
	s_mov_b32 s25, s45
	s_cbranch_vccnz .LBB0_269
	s_mul_i32 s2, s23, s65
	s_mul_i32 s3, s72, s86
	s_add_i32 s25, s3, s2
	s_lshr_b32 s32, s86, 2
	s_sub_i32 s32, s32, 1
	s_max_i32 s32, s32, 0
	s_lshl_b32 s32, s32, 8
	s_cmp_eq_u32 s16, 3
	s_cselect_b32 s32, s32, 0
	s_add_i32 s25, s25, s32
.LBB0_269:
	s_mul_i32 s22, s86, s9
	s_lshr_b32 s32, s86, 2
	s_sub_i32 s32, s32, 1
	s_max_i32 s32, s32, 0
	s_lshl_b32 s32, s32, 8
	s_cmp_eq_u32 s16, 3
	s_cselect_b32 s32, s32, 0
	s_add_i32 s22, s22, s32
	s_mov_b32 s101, s54
	s_cmp_eq_u32 s16, 3
	s_cbranch_scc0 .Lkt_nt
	s_lshr_b32 s32, s33, 2
	s_cmp_eq_u32 s32, 2
	s_cselect_b32 s101, 4, 2
.Lkt_nt:
	s_add_i32 s100, s101, -2
	s_and_b64 s[2:3], s[42:43], exec
	v_mov_b32_e32 v0, 0
	s_cselect_b32 s2, s22, s44
	s_add_i32 s3, s45, 0x80
	s_add_i32 s42, s44, 0x100
	s_mov_b32 s43, 0
	v_mov_b32_e32 v1, v0
	v_mov_b32_e32 v2, v0
	v_mov_b32_e32 v3, v0
	v_mov_b32_e32 v4, v0
	v_mov_b32_e32 v5, v0
	v_mov_b32_e32 v6, v0
	v_mov_b32_e32 v7, v0
	v_mov_b32_e32 v16, v0
	v_mov_b32_e32 v17, v0
	v_mov_b32_e32 v18, v0
	v_mov_b32_e32 v19, v0
	v_mov_b32_e32 v20, v0
	v_mov_b32_e32 v21, v0
	v_mov_b32_e32 v22, v0
	v_mov_b32_e32 v23, v0
	v_mov_b32_e32 v32, v0
	v_mov_b32_e32 v33, v0
	v_mov_b32_e32 v34, v0
	v_mov_b32_e32 v35, v0
	v_mov_b32_e32 v36, v0
	v_mov_b32_e32 v37, v0
	v_mov_b32_e32 v38, v0
	v_mov_b32_e32 v39, v0
	v_mov_b32_e32 v48, v0
	v_mov_b32_e32 v49, v0
	v_mov_b32_e32 v50, v0
	v_mov_b32_e32 v51, v0
	v_mov_b32_e32 v52, v0
	v_mov_b32_e32 v53, v0
	v_mov_b32_e32 v54, v0
	v_mov_b32_e32 v55, v0
	v_mov_b32_e32 v8, v0
	v_mov_b32_e32 v9, v0
	v_mov_b32_e32 v10, v0
	v_mov_b32_e32 v11, v0
	v_mov_b32_e32 v12, v0
	v_mov_b32_e32 v13, v0
	v_mov_b32_e32 v14, v0
	v_mov_b32_e32 v15, v0
	v_mov_b32_e32 v24, v0
	v_mov_b32_e32 v25, v0
	v_mov_b32_e32 v26, v0
	v_mov_b32_e32 v27, v0
	v_mov_b32_e32 v28, v0
	v_mov_b32_e32 v29, v0
	v_mov_b32_e32 v30, v0
	v_mov_b32_e32 v31, v0
	v_mov_b32_e32 v40, v0
	v_mov_b32_e32 v41, v0
	v_mov_b32_e32 v42, v0
	v_mov_b32_e32 v43, v0
	v_mov_b32_e32 v44, v0
	v_mov_b32_e32 v45, v0
	v_mov_b32_e32 v46, v0
	v_mov_b32_e32 v47, v0
	v_mov_b32_e32 v56, v0
	v_mov_b32_e32 v57, v0
	v_mov_b32_e32 v58, v0
	v_mov_b32_e32 v59, v0
	v_mov_b32_e32 v60, v0
	v_mov_b32_e32 v61, v0
	v_mov_b32_e32 v62, v0
	v_mov_b32_e32 v63, v0
	v_mov_b32_e32 v64, v0
	v_mov_b32_e32 v65, v0
	v_mov_b32_e32 v66, v0
	v_mov_b32_e32 v67, v0
	v_mov_b32_e32 v68, v0
	v_mov_b32_e32 v69, v0
	v_mov_b32_e32 v70, v0
	v_mov_b32_e32 v71, v0
	v_mov_b32_e32 v80, v0
	v_mov_b32_e32 v81, v0
	v_mov_b32_e32 v82, v0
	v_mov_b32_e32 v83, v0
	v_mov_b32_e32 v84, v0
	v_mov_b32_e32 v85, v0
	v_mov_b32_e32 v86, v0
	v_mov_b32_e32 v87, v0
	v_mov_b32_e32 v96, v0
	v_mov_b32_e32 v97, v0
	v_mov_b32_e32 v98, v0
	v_mov_b32_e32 v99, v0
	v_mov_b32_e32 v100, v0
	v_mov_b32_e32 v101, v0
	v_mov_b32_e32 v102, v0
	v_mov_b32_e32 v103, v0
	v_mov_b32_e32 v112, v0
	v_mov_b32_e32 v113, v0
	v_mov_b32_e32 v114, v0
	v_mov_b32_e32 v115, v0
	v_mov_b32_e32 v116, v0
	v_mov_b32_e32 v117, v0
	v_mov_b32_e32 v118, v0
	v_mov_b32_e32 v119, v0
	v_mov_b32_e32 v72, v0
	v_mov_b32_e32 v73, v0
	v_mov_b32_e32 v74, v0
	v_mov_b32_e32 v75, v0
	v_mov_b32_e32 v76, v0
	v_mov_b32_e32 v77, v0
	v_mov_b32_e32 v78, v0
	v_mov_b32_e32 v79, v0
	v_mov_b32_e32 v88, v0
	v_mov_b32_e32 v89, v0
	v_mov_b32_e32 v90, v0
	v_mov_b32_e32 v91, v0
	v_mov_b32_e32 v92, v0
	v_mov_b32_e32 v93, v0
	v_mov_b32_e32 v94, v0
	v_mov_b32_e32 v95, v0
	v_mov_b32_e32 v104, v0
	v_mov_b32_e32 v105, v0
	v_mov_b32_e32 v106, v0
	v_mov_b32_e32 v107, v0
	v_mov_b32_e32 v108, v0
	v_mov_b32_e32 v109, v0
	v_mov_b32_e32 v110, v0
	v_mov_b32_e32 v111, v0
	v_mov_b32_e32 v120, v0
	v_mov_b32_e32 v121, v0
	v_mov_b32_e32 v122, v0
	v_mov_b32_e32 v123, v0
	v_mov_b32_e32 v124, v0
	v_mov_b32_e32 v125, v0
	v_mov_b32_e32 v126, v0
	v_mov_b32_e32 v127, v0
.LBB0_270:
	v_add_u32_e32 v140, 0x10000, v223
	v_add_u32_e32 v156, 0x14000, v223
	s_waitcnt lgkmcnt(0)
	ds_read_b128 v[128:131], v140
	ds_read_b128 v[132:135], v140 offset:1024
	ds_read_b128 v[136:139], v140 offset:2048
	ds_read_b128 v[140:143], v140 offset:3072
	ds_read_b128 v[144:147], v156
	ds_read_b128 v[148:151], v156 offset:1024
	ds_read_b128 v[152:155], v156 offset:2048
	ds_read_b128 v[182:185], v156 offset:3072
	s_add_i32 s44, s3, 0x80
	s_cmp_eq_u32 s100, s43
	s_cselect_b32 s45, s25, s44
	s_cselect_b32 s90, s2, s42
	s_add_i32 s44, s45, 0x80
	s_add_i32 s48, s73, s3
	s_mov_b32 s76, s46
	s_mov_b32 m0, s96
	ds_read_b128 v[186:189], v224
	ds_read_b128 v[190:193], v224 offset:1024
	ds_read_b128 v[232:235], v224 offset:2048
	ds_read_b128 v[236:239], v224 offset:3072
	ds_read_b128 v[240:243], v224 offset:4096
	ds_read_b128 v[244:247], v224 offset:5120
	ds_read_b128 v[248:251], v224 offset:6144
	ds_read_b128 v[202:205], v224 offset:7168
	buffer_load_dwordx4 v217, s[76:79], s48 offen lds
	s_mov_b32 m0, s97
	s_nop 0
	buffer_load_dwordx4 v219, s[76:79], s48 offen lds
	s_waitcnt vmcnt(8)
	s_waitcnt lgkmcnt(0)
	s_barrier
	s_setprio 1
	s_waitcnt lgkmcnt(7)
	v_mfma_f32_16x16x32_bf16 v[124:127], v[128:131], v[186:189], v[124:127]
	v_mfma_f32_16x16x32_bf16 v[120:123], v[136:139], v[186:189], v[120:123]
	s_waitcnt lgkmcnt(5)
	v_mfma_f32_16x16x32_bf16 v[108:111], v[128:131], v[232:235], v[108:111]
	v_mfma_f32_16x16x32_bf16 v[104:107], v[136:139], v[232:235], v[104:107]
	s_waitcnt lgkmcnt(3)
	v_mfma_f32_16x16x32_bf16 v[92:95], v[128:131], v[240:243], v[92:95]
	v_mfma_f32_16x16x32_bf16 v[88:91], v[136:139], v[240:243], v[88:91]
	s_waitcnt lgkmcnt(1)
	v_mfma_f32_16x16x32_bf16 v[76:79], v[128:131], v[248:251], v[76:79]
	v_mfma_f32_16x16x32_bf16 v[72:75], v[136:139], v[248:251], v[72:75]
	v_mfma_f32_16x16x32_bf16 v[124:127], v[132:135], v[190:193], v[124:127]
	v_mfma_f32_16x16x32_bf16 v[120:123], v[140:143], v[190:193], v[120:123]
	v_mfma_f32_16x16x32_bf16 v[108:111], v[132:135], v[236:239], v[108:111]
	v_mfma_f32_16x16x32_bf16 v[104:107], v[140:143], v[236:239], v[104:107]
	v_mfma_f32_16x16x32_bf16 v[92:95], v[132:135], v[244:247], v[92:95]
	v_mfma_f32_16x16x32_bf16 v[88:91], v[140:143], v[244:247], v[88:91]
	s_waitcnt lgkmcnt(0)
	v_mfma_f32_16x16x32_bf16 v[76:79], v[132:135], v[202:205], v[76:79]
	v_mfma_f32_16x16x32_bf16 v[72:75], v[140:143], v[202:205], v[72:75]
	s_setprio 0
	s_setprio 1
	v_mfma_f32_16x16x32_bf16 v[116:119], v[144:147], v[186:189], v[116:119]
	v_mfma_f32_16x16x32_bf16 v[112:115], v[152:155], v[186:189], v[112:115]
	v_mfma_f32_16x16x32_bf16 v[100:103], v[144:147], v[232:235], v[100:103]
	v_mfma_f32_16x16x32_bf16 v[96:99], v[152:155], v[232:235], v[96:99]
	v_mfma_f32_16x16x32_bf16 v[84:87], v[144:147], v[240:243], v[84:87]
	v_mfma_f32_16x16x32_bf16 v[80:83], v[152:155], v[240:243], v[80:83]
	v_mfma_f32_16x16x32_bf16 v[68:71], v[144:147], v[248:251], v[68:71]
	v_mfma_f32_16x16x32_bf16 v[64:67], v[152:155], v[248:251], v[64:67]
	v_mfma_f32_16x16x32_bf16 v[116:119], v[148:151], v[190:193], v[116:119]
	v_mfma_f32_16x16x32_bf16 v[112:115], v[182:185], v[190:193], v[112:115]
	v_mfma_f32_16x16x32_bf16 v[100:103], v[148:151], v[236:239], v[100:103]
	v_mfma_f32_16x16x32_bf16 v[96:99], v[182:185], v[236:239], v[96:99]
	v_mfma_f32_16x16x32_bf16 v[84:87], v[148:151], v[244:247], v[84:87]
	v_mfma_f32_16x16x32_bf16 v[80:83], v[182:185], v[244:247], v[80:83]
	v_mfma_f32_16x16x32_bf16 v[68:71], v[148:151], v[202:205], v[68:71]
	v_mfma_f32_16x16x32_bf16 v[64:67], v[182:185], v[202:205], v[64:67]
	s_setprio 0
	s_barrier
	s_mov_b32 m0, s71
	s_mov_b32 s48, s94
	s_mov_b32 s50, s78
	s_mov_b32 s51, s79
	ds_read_b128 v[186:189], v224 offset:16384
	ds_read_b128 v[190:193], v224 offset:17408
	ds_read_b128 v[202:205], v224 offset:18432
	ds_read_b128 v[232:235], v224 offset:19456
	ds_read_b128 v[236:239], v224 offset:20480
	ds_read_b128 v[240:243], v224 offset:21504
	ds_read_b128 v[244:247], v224 offset:22528
	ds_read_b128 v[248:251], v224 offset:23552
	buffer_load_dwordx4 v218, s[48:51], s90 offen lds
	s_mov_b32 m0, s28
	s_add_i32 s91, s90, s64
	buffer_load_dwordx4 v220, s[48:51], s90 offen lds
	s_mov_b32 m0, s29
	s_nop 0
	buffer_load_dwordx4 v218, s[48:51], s91 offen lds
	s_mov_b32 m0, s26
	s_nop 0
	buffer_load_dwordx4 v220, s[48:51], s91 offen lds
	s_mov_b32 m0, s70
	s_nop 0
	buffer_load_dwordx4 v217, s[76:79], s45 offen lds
	s_mov_b32 m0, s27
	s_nop 0
	buffer_load_dwordx4 v219, s[76:79], s45 offen lds
	s_waitcnt vmcnt(8)
	s_waitcnt lgkmcnt(0)
	s_barrier
	s_setprio 1
	s_waitcnt lgkmcnt(7)
	v_mfma_f32_16x16x32_bf16 v[60:63], v[128:131], v[186:189], v[60:63]
	v_mfma_f32_16x16x32_bf16 v[56:59], v[136:139], v[186:189], v[56:59]
	s_waitcnt lgkmcnt(5)
	v_mfma_f32_16x16x32_bf16 v[44:47], v[128:131], v[202:205], v[44:47]
	v_mfma_f32_16x16x32_bf16 v[40:43], v[136:139], v[202:205], v[40:43]
	s_waitcnt lgkmcnt(3)
	v_mfma_f32_16x16x32_bf16 v[28:31], v[128:131], v[236:239], v[28:31]
	v_mfma_f32_16x16x32_bf16 v[24:27], v[136:139], v[236:239], v[24:27]
	s_waitcnt lgkmcnt(1)
	v_mfma_f32_16x16x32_bf16 v[12:15], v[128:131], v[244:247], v[12:15]
	v_mfma_f32_16x16x32_bf16 v[8:11], v[136:139], v[244:247], v[8:11]
	v_mfma_f32_16x16x32_bf16 v[60:63], v[132:135], v[190:193], v[60:63]
	v_mfma_f32_16x16x32_bf16 v[56:59], v[140:143], v[190:193], v[56:59]
	v_mfma_f32_16x16x32_bf16 v[44:47], v[132:135], v[232:235], v[44:47]
	v_mfma_f32_16x16x32_bf16 v[40:43], v[140:143], v[232:235], v[40:43]
	v_mfma_f32_16x16x32_bf16 v[28:31], v[132:135], v[240:243], v[28:31]
	v_mfma_f32_16x16x32_bf16 v[24:27], v[140:143], v[240:243], v[24:27]
	s_waitcnt lgkmcnt(0)
	v_mfma_f32_16x16x32_bf16 v[12:15], v[132:135], v[248:251], v[12:15]
	v_mfma_f32_16x16x32_bf16 v[8:11], v[140:143], v[248:251], v[8:11]
	s_setprio 0
	s_setprio 1
	v_mfma_f32_16x16x32_bf16 v[52:55], v[144:147], v[186:189], v[52:55]
	v_mfma_f32_16x16x32_bf16 v[48:51], v[152:155], v[186:189], v[48:51]
	v_mfma_f32_16x16x32_bf16 v[36:39], v[144:147], v[202:205], v[36:39]
	v_mfma_f32_16x16x32_bf16 v[32:35], v[152:155], v[202:205], v[32:35]
	v_mfma_f32_16x16x32_bf16 v[20:23], v[144:147], v[236:239], v[20:23]
	v_mfma_f32_16x16x32_bf16 v[16:19], v[152:155], v[236:239], v[16:19]
	v_mfma_f32_16x16x32_bf16 v[4:7], v[144:147], v[244:247], v[4:7]
	v_mfma_f32_16x16x32_bf16 v[0:3], v[152:155], v[244:247], v[0:3]
	v_mfma_f32_16x16x32_bf16 v[52:55], v[148:151], v[190:193], v[52:55]
	v_mfma_f32_16x16x32_bf16 v[48:51], v[182:185], v[190:193], v[48:51]
	v_mfma_f32_16x16x32_bf16 v[36:39], v[148:151], v[232:235], v[36:39]
	v_mfma_f32_16x16x32_bf16 v[32:35], v[182:185], v[232:235], v[32:35]
	v_mfma_f32_16x16x32_bf16 v[20:23], v[148:151], v[240:243], v[20:23]
	v_mfma_f32_16x16x32_bf16 v[16:19], v[182:185], v[240:243], v[16:19]
	v_mfma_f32_16x16x32_bf16 v[4:7], v[148:151], v[248:251], v[4:7]
	v_mfma_f32_16x16x32_bf16 v[0:3], v[182:185], v[248:251], v[0:3]
	s_setprio 0
	s_barrier
	v_add_u32_e32 v140, 0x18000, v223
	v_add_u32_e32 v156, 0x1c000, v223
	ds_read_b128 v[128:131], v140
	ds_read_b128 v[132:135], v140 offset:1024
	ds_read_b128 v[136:139], v140 offset:2048
	ds_read_b128 v[140:143], v140 offset:3072
	ds_read_b128 v[144:147], v156
	ds_read_b128 v[148:151], v156 offset:1024
	ds_read_b128 v[152:155], v156 offset:2048
	ds_read_b128 v[182:185], v156 offset:3072
	s_add_i32 s45, s45, s73
	s_mov_b32 m0, s62
	ds_read_b128 v[186:189], v224 offset:32768
	ds_read_b128 v[190:193], v224 offset:33792
	ds_read_b128 v[202:205], v224 offset:34816
	ds_read_b128 v[232:235], v224 offset:35840
	ds_read_b128 v[236:239], v224 offset:36864
	ds_read_b128 v[240:243], v224 offset:37888
	ds_read_b128 v[244:247], v224 offset:38912
	ds_read_b128 v[248:251], v224 offset:39936
	buffer_load_dwordx4 v217, s[76:79], s45 offen lds
	s_mov_b32 m0, s63
	s_nop 0
	buffer_load_dwordx4 v219, s[76:79], s45 offen lds
	s_waitcnt vmcnt(8)
	s_waitcnt lgkmcnt(0)
	s_barrier
	s_setprio 1
	s_waitcnt lgkmcnt(7)
	v_mfma_f32_16x16x32_bf16 v[124:127], v[128:131], v[186:189], v[124:127]
	v_mfma_f32_16x16x32_bf16 v[120:123], v[136:139], v[186:189], v[120:123]
	s_waitcnt lgkmcnt(5)
	v_mfma_f32_16x16x32_bf16 v[108:111], v[128:131], v[202:205], v[108:111]
	v_mfma_f32_16x16x32_bf16 v[104:107], v[136:139], v[202:205], v[104:107]
	s_waitcnt lgkmcnt(3)
	v_mfma_f32_16x16x32_bf16 v[92:95], v[128:131], v[236:239], v[92:95]
	v_mfma_f32_16x16x32_bf16 v[88:91], v[136:139], v[236:239], v[88:91]
	s_waitcnt lgkmcnt(1)
	v_mfma_f32_16x16x32_bf16 v[76:79], v[128:131], v[244:247], v[76:79]
	v_mfma_f32_16x16x32_bf16 v[72:75], v[136:139], v[244:247], v[72:75]
	v_mfma_f32_16x16x32_bf16 v[124:127], v[132:135], v[190:193], v[124:127]
	v_mfma_f32_16x16x32_bf16 v[120:123], v[140:143], v[190:193], v[120:123]
	v_mfma_f32_16x16x32_bf16 v[108:111], v[132:135], v[232:235], v[108:111]
	v_mfma_f32_16x16x32_bf16 v[104:107], v[140:143], v[232:235], v[104:107]
	v_mfma_f32_16x16x32_bf16 v[92:95], v[132:135], v[240:243], v[92:95]
	v_mfma_f32_16x16x32_bf16 v[88:91], v[140:143], v[240:243], v[88:91]
	s_waitcnt lgkmcnt(0)
	v_mfma_f32_16x16x32_bf16 v[76:79], v[132:135], v[248:251], v[76:79]
	v_mfma_f32_16x16x32_bf16 v[72:75], v[140:143], v[248:251], v[72:75]
	s_setprio 0
	s_setprio 1
	v_mfma_f32_16x16x32_bf16 v[116:119], v[144:147], v[186:189], v[116:119]
	v_mfma_f32_16x16x32_bf16 v[112:115], v[152:155], v[186:189], v[112:115]
	v_mfma_f32_16x16x32_bf16 v[100:103], v[144:147], v[202:205], v[100:103]
	v_mfma_f32_16x16x32_bf16 v[96:99], v[152:155], v[202:205], v[96:99]
	v_mfma_f32_16x16x32_bf16 v[84:87], v[144:147], v[236:239], v[84:87]
	v_mfma_f32_16x16x32_bf16 v[80:83], v[152:155], v[236:239], v[80:83]
	v_mfma_f32_16x16x32_bf16 v[68:71], v[144:147], v[244:247], v[68:71]
	v_mfma_f32_16x16x32_bf16 v[64:67], v[152:155], v[244:247], v[64:67]
	v_mfma_f32_16x16x32_bf16 v[116:119], v[148:151], v[190:193], v[116:119]
	v_mfma_f32_16x16x32_bf16 v[112:115], v[182:185], v[190:193], v[112:115]
	v_mfma_f32_16x16x32_bf16 v[100:103], v[148:151], v[232:235], v[100:103]
	v_mfma_f32_16x16x32_bf16 v[96:99], v[182:185], v[232:235], v[96:99]
	v_mfma_f32_16x16x32_bf16 v[84:87], v[148:151], v[240:243], v[84:87]
	v_mfma_f32_16x16x32_bf16 v[80:83], v[182:185], v[240:243], v[80:83]
	v_mfma_f32_16x16x32_bf16 v[68:71], v[148:151], v[248:251], v[68:71]
	v_mfma_f32_16x16x32_bf16 v[64:67], v[182:185], v[248:251], v[64:67]
	s_setprio 0
	s_barrier
	s_mov_b32 m0, s88
	s_add_i32 s45, s90, 0x80
	ds_read_b128 v[186:189], v224 offset:49152
	ds_read_b128 v[190:193], v224 offset:50176
	ds_read_b128 v[202:205], v224 offset:51200
	ds_read_b128 v[232:235], v224 offset:52224
	ds_read_b128 v[236:239], v224 offset:53248
	ds_read_b128 v[240:243], v224 offset:54272
	ds_read_b128 v[244:247], v224 offset:55296
	ds_read_b128 v[248:251], v224 offset:56320
	buffer_load_dwordx4 v218, s[48:51], s45 offen lds
	s_mov_b32 m0, s82
	s_nop 0
	buffer_load_dwordx4 v220, s[48:51], s45 offen lds
	s_add_i32 s45, s45, s64
	s_mov_b32 m0, s58
	s_nop 0
	buffer_load_dwordx4 v218, s[48:51], s45 offen lds
	s_mov_b32 m0, s59
	s_nop 0
	buffer_load_dwordx4 v220, s[48:51], s45 offen lds
	s_mov_b32 m0, s83
	s_nop 0
	buffer_load_dwordx4 v217, s[76:79], s44 offen lds
	s_mov_b32 m0, s89
	s_nop 0
	buffer_load_dwordx4 v219, s[76:79], s44 offen lds
	s_waitcnt vmcnt(8)
	s_waitcnt lgkmcnt(0)
	s_barrier
	s_setprio 1
	s_waitcnt lgkmcnt(7)
	v_mfma_f32_16x16x32_bf16 v[60:63], v[128:131], v[186:189], v[60:63]
	v_mfma_f32_16x16x32_bf16 v[56:59], v[136:139], v[186:189], v[56:59]
	s_waitcnt lgkmcnt(5)
	v_mfma_f32_16x16x32_bf16 v[44:47], v[128:131], v[202:205], v[44:47]
	v_mfma_f32_16x16x32_bf16 v[40:43], v[136:139], v[202:205], v[40:43]
	s_waitcnt lgkmcnt(3)
	v_mfma_f32_16x16x32_bf16 v[28:31], v[128:131], v[236:239], v[28:31]
	v_mfma_f32_16x16x32_bf16 v[24:27], v[136:139], v[236:239], v[24:27]
	s_waitcnt lgkmcnt(1)
	v_mfma_f32_16x16x32_bf16 v[12:15], v[128:131], v[244:247], v[12:15]
	v_mfma_f32_16x16x32_bf16 v[8:11], v[136:139], v[244:247], v[8:11]
	v_mfma_f32_16x16x32_bf16 v[60:63], v[132:135], v[190:193], v[60:63]
	v_mfma_f32_16x16x32_bf16 v[56:59], v[140:143], v[190:193], v[56:59]
	v_mfma_f32_16x16x32_bf16 v[44:47], v[132:135], v[232:235], v[44:47]
	v_mfma_f32_16x16x32_bf16 v[40:43], v[140:143], v[232:235], v[40:43]
	v_mfma_f32_16x16x32_bf16 v[28:31], v[132:135], v[240:243], v[28:31]
	v_mfma_f32_16x16x32_bf16 v[24:27], v[140:143], v[240:243], v[24:27]
	s_waitcnt lgkmcnt(0)
	v_mfma_f32_16x16x32_bf16 v[12:15], v[132:135], v[248:251], v[12:15]
	v_mfma_f32_16x16x32_bf16 v[8:11], v[140:143], v[248:251], v[8:11]
	s_setprio 0
	s_setprio 1
	v_mfma_f32_16x16x32_bf16 v[52:55], v[144:147], v[186:189], v[52:55]
	v_mfma_f32_16x16x32_bf16 v[48:51], v[152:155], v[186:189], v[48:51]
	v_mfma_f32_16x16x32_bf16 v[36:39], v[144:147], v[202:205], v[36:39]
	v_mfma_f32_16x16x32_bf16 v[32:35], v[152:155], v[202:205], v[32:35]
	v_mfma_f32_16x16x32_bf16 v[20:23], v[144:147], v[236:239], v[20:23]
	v_mfma_f32_16x16x32_bf16 v[16:19], v[152:155], v[236:239], v[16:19]
	v_mfma_f32_16x16x32_bf16 v[4:7], v[144:147], v[244:247], v[4:7]
	v_mfma_f32_16x16x32_bf16 v[0:3], v[152:155], v[244:247], v[0:3]
	v_mfma_f32_16x16x32_bf16 v[52:55], v[148:151], v[190:193], v[52:55]
	v_mfma_f32_16x16x32_bf16 v[48:51], v[182:185], v[190:193], v[48:51]
	v_mfma_f32_16x16x32_bf16 v[36:39], v[148:151], v[232:235], v[36:39]
	v_mfma_f32_16x16x32_bf16 v[32:35], v[182:185], v[232:235], v[32:35]
	v_mfma_f32_16x16x32_bf16 v[20:23], v[148:151], v[240:243], v[20:23]
	v_mfma_f32_16x16x32_bf16 v[16:19], v[182:185], v[240:243], v[16:19]
	v_mfma_f32_16x16x32_bf16 v[4:7], v[148:151], v[248:251], v[4:7]
	v_mfma_f32_16x16x32_bf16 v[0:3], v[182:185], v[248:251], v[0:3]
	s_setprio 0
	s_barrier
	s_add_i32 s43, s43, 2
	s_addk_i32 s3, 0x100
	s_addk_i32 s42, 0x100
	s_cmp_ge_i32 s43, s101
	s_cbranch_scc0 .LBB0_270
	s_and_b64 vcc, exec, s[20:21]
	s_cbranch_vccz .LBB0_273
	s_barrier

	.amdhsa_kernel _Z14fwd_megakernel4Args
		.amdhsa_group_segment_fixed_size 0
		.amdhsa_private_segment_fixed_size 0
		.amdhsa_kernarg_size 512
		.amdhsa_user_sgpr_count 2
		.amdhsa_user_sgpr_dispatch_ptr 0
		.amdhsa_user_sgpr_queue_ptr 0
		.amdhsa_user_sgpr_kernarg_segment_ptr 1
		.amdhsa_user_sgpr_dispatch_id 0
		.amdhsa_user_sgpr_kernarg_preload_length 0
		.amdhsa_user_sgpr_kernarg_preload_offset 0
		.amdhsa_user_sgpr_private_segment_size 0
		.amdhsa_uses_dynamic_stack 0
		.amdhsa_enable_private_segment 0
		.amdhsa_system_sgpr_workgroup_id_x 1
		.amdhsa_system_sgpr_workgroup_id_y 0
		.amdhsa_system_sgpr_workgroup_id_z 0
		.amdhsa_system_sgpr_workgroup_info 0
		.amdhsa_system_vgpr_workitem_id 2
		.amdhsa_next_free_vgpr 256
		.amdhsa_next_free_sgpr 102
		.amdhsa_accum_offset 256
		.amdhsa_reserve_vcc 1
		.amdhsa_float_round_mode_32 0
		.amdhsa_float_round_mode_16_64 0
		.amdhsa_float_denorm_mode_32 3
		.amdhsa_float_denorm_mode_16_64 3
		.amdhsa_dx10_clamp 1
		.amdhsa_ieee_mode 1
		.amdhsa_fp16_overflow 0
		.amdhsa_tg_split 0
		.amdhsa_exception_fp_ieee_invalid_op 0
		.amdhsa_exception_fp_denorm_src 0
		.amdhsa_exception_fp_ieee_div_zero 0
		.amdhsa_exception_fp_ieee_overflow 0
		.amdhsa_exception_fp_ieee_underflow 0
		.amdhsa_exception_fp_ieee_inexact 0
		.amdhsa_exception_int_div_zero 0
	.end_amdhsa_kernel

amdhsa.kernels:
  - .agpr_count:     0
    .args:
      - .offset:         0
        .size:           256
        .value_kind:     by_value
      - .offset:         256
        .size:           4
        .value_kind:     hidden_block_count_x
      - .offset:         260
        .size:           4
        .value_kind:     hidden_block_count_y
      - .offset:         264
        .size:           4
        .value_kind:     hidden_block_count_z
      - .offset:         268
        .size:           2
        .value_kind:     hidden_group_size_x
      - .offset:         270
        .size:           2
        .value_kind:     hidden_group_size_y
      - .offset:         272
        .size:           2
        .value_kind:     hidden_group_size_z
      - .offset:         274
        .size:           2
        .value_kind:     hidden_remainder_x
      - .offset:         276
        .size:           2
        .value_kind:     hidden_remainder_y
      - .offset:         278
        .size:           2
        .value_kind:     hidden_remainder_z
      - .offset:         296
        .size:           8
        .value_kind:     hidden_global_offset_x
      - .offset:         304
        .size:           8
        .value_kind:     hidden_global_offset_y
      - .offset:         312
        .size:           8
        .value_kind:     hidden_global_offset_z
      - .offset:         320
        .size:           2
        .value_kind:     hidden_grid_dims
      - .offset:         344
        .size:           8
        .value_kind:     hidden_multigrid_sync_arg
      - .offset:         376
        .size:           4
        .value_kind:     hidden_dynamic_lds_size
    .group_segment_fixed_size: 0
    .kernarg_segment_align: 8
    .kernarg_segment_size: 512
    .language:       OpenCL C
    .language_version:
      - 2
      - 0
    .max_flat_workgroup_size: 512
    .name:           _Z14fwd_megakernel4Args
    .private_segment_fixed_size: 0
    .sgpr_count:     108
    .sgpr_spill_count: 181
    .symbol:         _Z14fwd_megakernel4Args.kd
    .uniform_work_group_size: 1
    .uses_dynamic_stack: false
    .vgpr_count:     256
    .vgpr_spill_count: 0
    .wavefront_size: 64
